# HGRN scan steps as in-place v_mul_f32_dpp (no 1.0 fill + mov_dpp + mul); LN-stat exchange invalidate before polling; seams early invalidate
# speedup vs baseline: 1.0042x; 1.0042x over previous
.LBB0_284:
	s_waitcnt vmcnt(3)
	v_mov_b64_e32 v[66:67], v[34:35]
	v_mov_b64_e32 v[64:65], v[32:33]
	s_waitcnt vmcnt(1)
	v_mov_b64_e32 v[70:71], v[38:39]
	v_mov_b64_e32 v[68:69], v[36:37]
	v_and_b32_e32 v34, 0xffff0000, v64
	v_and_b32_e32 v35, 0xffff0000, v68
	v_mul_f32_e64 v32, |v34|, s45
	v_exp_f32_e32 v33, v32
	v_mul_f32_e64 v32, |v35|, s45
	v_exp_f32_e32 v32, v32
	v_cmp_le_f32_e64 s[4:5], 0, v34
	v_add_f32_e32 v36, 1.0, v33
	v_rcp_f32_e32 v123, v36
	v_add_f32_e32 v36, 1.0, v32
	v_rcp_f32_e32 v122, v36
	v_cmp_le_f32_e64 s[6:7], 0, v35
	v_lshlrev_b32_e32 v37, 16, v65
	v_pk_mul_f32 v[124:125], v[32:33], v[122:123]
	v_lshlrev_b32_e32 v36, 16, v69
	v_cndmask_b32_e64 v33, v125, v123, s[4:5]
	v_cndmask_b32_e64 v32, v124, v122, s[6:7]
	v_pk_fma_f32 v[32:33], v[98:99], v[32:33], v[120:121]
	v_cmp_le_f32_e64 s[8:9], 0, v37
	v_mul_f32_e32 v32, v32, v33
	v_cmp_le_f32_e64 s[10:11], 0, v36
	v_lshlrev_b32_e32 v68, 16, v68
	v_mul_f32_dpp v32, v32, v32 row_shr:1 row_mask:0xf bank_mask:0xf
	v_lshlrev_b32_e32 v64, 16, v64
	v_cndmask_b32_e64 v123, v123, v125, s[4:5]
	v_mul_f32_dpp v32, v32, v32 row_shr:2 row_mask:0xf bank_mask:0xf
	v_cndmask_b32_e64 v122, v122, v124, s[6:7]
	v_pk_mul_f32 v[122:123], v[98:99], v[122:123]
	v_mul_f32_dpp v32, v32, v32 row_shr:4 row_mask:0xf bank_mask:0xf
	s_nop 1
	v_mul_f32_dpp v32, v32, v32 row_shr:8 row_mask:0xf bank_mask:0xf
	v_mov_b32_e32 v34, 1.0
	s_nop 1
	v_mov_b32_dpp v34, v32 row_bcast:15 row_mask:0xa bank_mask:0xf
	v_mul_f32_e32 v74, v32, v34
	v_mul_f32_e64 v34, |v37|, s45
	v_exp_f32_e32 v35, v34
	v_mul_f32_e64 v34, |v36|, s45
	v_exp_f32_e32 v34, v34
	v_mov_b32_e32 v32, 1.0
	v_add_f32_e32 v38, 1.0, v35
	v_rcp_f32_e32 v127, v38
	v_add_f32_e32 v38, 1.0, v34
	v_rcp_f32_e32 v126, v38
	v_mov_b32_dpp v32, v74 wave_shr:1 row_mask:0xf bank_mask:0xf
	v_cndmask_b32_e64 v32, v32, 1.0, s[0:1]
	v_mul_f32_e32 v56, v33, v32
	v_pk_mul_f32 v[128:129], v[34:35], v[126:127]
	v_cndmask_b32_e64 v33, v129, v127, s[8:9]
	v_cndmask_b32_e64 v32, v128, v126, s[10:11]
	v_pk_fma_f32 v[32:33], v[96:97], v[32:33], v[114:115]
	v_and_b32_e32 v36, 0xffff0000, v65
	v_mul_f32_e32 v32, v32, v33
	v_and_b32_e32 v37, 0xffff0000, v69
	v_cmp_le_f32_e64 s[12:13], 0, v36
	v_mul_f32_dpp v32, v32, v32 row_shr:1 row_mask:0xf bank_mask:0xf
	v_cmp_le_f32_e64 s[14:15], 0, v37
	v_rcp_f32_e32 v65, v56
	v_mul_f32_dpp v32, v32, v32 row_shr:2 row_mask:0xf bank_mask:0xf
	v_mul_f32_e64 v56, |v64|, s45
	v_exp_f32_e32 v56, v56
	v_mul_f32_dpp v32, v32, v32 row_shr:4 row_mask:0xf bank_mask:0xf
	v_add_f32_e32 v168, 1.0, v56
	v_rcp_f32_e32 v168, v168
	v_mul_f32_dpp v32, v32, v32 row_shr:8 row_mask:0xf bank_mask:0xf
	v_mov_b32_e32 v34, 1.0
	v_readlane_b32 s42, v74, 31
	v_readlane_b32 s50, v74, 63
	v_mov_b32_dpp v34, v32 row_bcast:15 row_mask:0xa bank_mask:0xf
	v_mul_f32_e32 v164, v32, v34
	v_mul_f32_e64 v34, |v36|, s45
	v_exp_f32_e32 v35, v34
	v_mul_f32_e64 v34, |v37|, s45
	v_exp_f32_e32 v34, v34
	v_mov_b32_e32 v32, 1.0
	v_add_f32_e32 v38, 1.0, v35
	v_rcp_f32_e32 v131, v38
	v_add_f32_e32 v38, 1.0, v34
	v_rcp_f32_e32 v130, v38
	v_mov_b32_dpp v32, v164 wave_shr:1 row_mask:0xf bank_mask:0xf
	v_cndmask_b32_e64 v32, v32, 1.0, s[0:1]
	v_mul_f32_e32 v57, v33, v32
	v_pk_mul_f32 v[132:133], v[34:35], v[130:131]
	v_cndmask_b32_e64 v33, v133, v131, s[12:13]
	v_cndmask_b32_e64 v32, v132, v130, s[14:15]
	v_pk_fma_f32 v[32:33], v[94:95], v[32:33], v[112:113]
	v_lshlrev_b32_e32 v37, 16, v66
	v_mul_f32_e32 v32, v32, v33
	v_lshlrev_b32_e32 v36, 16, v70
	v_readlane_b32 s16, v164, 31
	v_mul_f32_dpp v32, v32, v32 row_shr:1 row_mask:0xf bank_mask:0xf
	v_readlane_b32 s17, v164, 63
	v_rcp_f32_e32 v69, v57
	v_mul_f32_dpp v32, v32, v32 row_shr:2 row_mask:0xf bank_mask:0xf
	v_mul_f32_e64 v57, |v68|, s45
	v_exp_f32_e32 v57, v57
	v_mul_f32_dpp v32, v32, v32 row_shr:4 row_mask:0xf bank_mask:0xf
	v_add_f32_e32 v169, 1.0, v57
	v_rcp_f32_e32 v169, v169
	v_mul_f32_dpp v32, v32, v32 row_shr:8 row_mask:0xf bank_mask:0xf
	v_mov_b32_e32 v34, 1.0
	v_pk_mul_f32 v[56:57], v[56:57], v[168:169]
	s_nop 0
	v_mov_b32_dpp v34, v32 row_bcast:15 row_mask:0xa bank_mask:0xf
	v_mul_f32_e32 v166, v32, v34
	v_mov_b32_e32 v32, 1.0
	v_readlane_b32 s18, v166, 31
	v_readlane_b32 s19, v166, 63
	v_mov_b32_dpp v32, v166 wave_shr:1 row_mask:0xf bank_mask:0xf
	v_cndmask_b32_e64 v32, v32, 1.0, s[0:1]
	v_mul_f32_e32 v165, v33, v32
	v_mul_f32_e64 v32, |v37|, s45
	v_exp_f32_e32 v33, v32
	v_mul_f32_e64 v32, |v36|, s45
	v_exp_f32_e32 v32, v32
	v_mov_b32_e32 v34, s19
	v_mov_b32_e32 v35, s18
	v_cndmask_b32_e64 v59, v34, v35, s[2:3]
	v_add_f32_e32 v34, 1.0, v33
	v_rcp_f32_e32 v135, v34
	v_add_f32_e32 v34, 1.0, v32
	v_rcp_f32_e32 v134, v34
	v_mov_b32_e32 v34, s17
	v_mov_b32_e32 v35, s16
	v_cmp_le_f32_e64 s[16:17], 0, v37
	v_pk_mul_f32 v[136:137], v[32:33], v[134:135]
	v_cmp_le_f32_e64 s[18:19], 0, v36
	v_cndmask_b32_e64 v33, v137, v135, s[16:17]
	v_cndmask_b32_e64 v58, v34, v35, s[2:3]
	v_cndmask_b32_e64 v32, v136, v134, s[18:19]
	v_pk_fma_f32 v[32:33], v[92:93], v[32:33], v[110:111]
	v_mul_f32_e32 v32, v32, v33
	v_and_b32_e32 v36, 0xffff0000, v66
	v_and_b32_e32 v37, 0xffff0000, v70
	v_mul_f32_dpp v32, v32, v32 row_shr:1 row_mask:0xf bank_mask:0xf
	v_cmp_le_f32_e64 s[20:21], 0, v36
	v_cmp_le_f32_e64 s[22:23], 0, v37
	v_mul_f32_dpp v32, v32, v32 row_shr:2 row_mask:0xf bank_mask:0xf
	v_rcp_f32_e32 v165, v165
	s_nop 0
	v_mul_f32_dpp v32, v32, v32 row_shr:4 row_mask:0xf bank_mask:0xf
	s_nop 1
	v_mul_f32_dpp v32, v32, v32 row_shr:8 row_mask:0xf bank_mask:0xf
	v_mov_b32_e32 v34, 1.0
	s_nop 1
	v_mov_b32_dpp v34, v32 row_bcast:15 row_mask:0xa bank_mask:0xf
	v_mul_f32_e32 v172, v32, v34
	v_mul_f32_e64 v34, |v36|, s45
	v_exp_f32_e32 v35, v34
	v_mul_f32_e64 v34, |v37|, s45
	v_exp_f32_e32 v34, v34
	v_mov_b32_e32 v32, 1.0
	v_add_f32_e32 v38, 1.0, v35
	v_rcp_f32_e32 v139, v38
	v_add_f32_e32 v38, 1.0, v34
	v_rcp_f32_e32 v138, v38
	v_mov_b32_dpp v32, v172 wave_shr:1 row_mask:0xf bank_mask:0xf
	v_cndmask_b32_e64 v32, v32, 1.0, s[0:1]
	v_mul_f32_e32 v167, v33, v32
	v_pk_mul_f32 v[140:141], v[34:35], v[138:139]
	v_cndmask_b32_e64 v33, v141, v139, s[20:21]
	v_cndmask_b32_e64 v32, v140, v138, s[22:23]
	v_pk_fma_f32 v[32:33], v[90:91], v[32:33], v[108:109]
	v_lshlrev_b32_e32 v37, 16, v67
	v_mul_f32_e32 v32, v32, v33
	v_lshlrev_b32_e32 v36, 16, v71
	v_readlane_b32 s24, v172, 31
	v_mul_f32_dpp v32, v32, v32 row_shr:1 row_mask:0xf bank_mask:0xf
	v_readlane_b32 s25, v172, 63
	v_rcp_f32_e32 v167, v167
	v_mul_f32_dpp v32, v32, v32 row_shr:2 row_mask:0xf bank_mask:0xf
	s_nop 1
	v_mul_f32_dpp v32, v32, v32 row_shr:4 row_mask:0xf bank_mask:0xf
	s_nop 1
	v_mul_f32_dpp v32, v32, v32 row_shr:8 row_mask:0xf bank_mask:0xf
	v_mov_b32_e32 v34, 1.0
	s_nop 1
	v_mov_b32_dpp v34, v32 row_bcast:15 row_mask:0xa bank_mask:0xf
	v_mul_f32_e32 v174, v32, v34
	v_mov_b32_e32 v32, 1.0
	v_readlane_b32 s26, v174, 31
	v_readlane_b32 s27, v174, 63
	v_mov_b32_dpp v32, v174 wave_shr:1 row_mask:0xf bank_mask:0xf
	v_cndmask_b32_e64 v32, v32, 1.0, s[0:1]
	v_mul_f32_e32 v173, v33, v32
	v_mul_f32_e64 v32, |v37|, s45
	v_exp_f32_e32 v33, v32
	v_mul_f32_e64 v32, |v36|, s45
	v_exp_f32_e32 v32, v32
	v_mov_b32_e32 v34, s27
	v_mov_b32_e32 v35, s26
	v_cndmask_b32_e64 v61, v34, v35, s[2:3]
	v_add_f32_e32 v34, 1.0, v33
	v_rcp_f32_e32 v161, v34
	v_add_f32_e32 v34, 1.0, v32
	v_rcp_f32_e32 v160, v34
	v_mov_b32_e32 v34, s25
	v_mov_b32_e32 v35, s24
	v_cmp_le_f32_e64 s[24:25], 0, v37
	v_pk_mul_f32 v[162:163], v[32:33], v[160:161]
	v_cmp_le_f32_e64 s[26:27], 0, v36
	v_cndmask_b32_e64 v33, v163, v161, s[24:25]
	v_cndmask_b32_e64 v60, v34, v35, s[2:3]
	v_cndmask_b32_e64 v32, v162, v160, s[26:27]
	v_pk_fma_f32 v[32:33], v[88:89], v[32:33], v[106:107]
	v_mul_f32_e32 v32, v32, v33
	v_and_b32_e32 v36, 0xffff0000, v67
	v_and_b32_e32 v37, 0xffff0000, v71
	v_mul_f32_dpp v32, v32, v32 row_shr:1 row_mask:0xf bank_mask:0xf
	v_cmp_le_f32_e64 s[28:29], 0, v36
	v_cmp_le_f32_e64 s[30:31], 0, v37
	v_mul_f32_dpp v32, v32, v32 row_shr:2 row_mask:0xf bank_mask:0xf
	v_rcp_f32_e32 v173, v173
	s_nop 0
	v_mul_f32_dpp v32, v32, v32 row_shr:4 row_mask:0xf bank_mask:0xf
	s_nop 1
	v_mul_f32_dpp v32, v32, v32 row_shr:8 row_mask:0xf bank_mask:0xf
	v_mov_b32_e32 v34, 1.0
	s_nop 1
	v_mov_b32_dpp v34, v32 row_bcast:15 row_mask:0xa bank_mask:0xf
	v_mul_f32_e32 v176, v32, v34
	v_mul_f32_e64 v34, |v36|, s45
	v_exp_f32_e32 v35, v34
	v_mul_f32_e64 v34, |v37|, s45
	v_exp_f32_e32 v34, v34
	v_mov_b32_e32 v32, 1.0
	v_add_f32_e32 v38, 1.0, v35
	v_rcp_f32_e32 v67, v38
	v_add_f32_e32 v38, 1.0, v34
	v_rcp_f32_e32 v66, v38
	v_mov_b32_dpp v32, v176 wave_shr:1 row_mask:0xf bank_mask:0xf
	v_cndmask_b32_e64 v32, v32, 1.0, s[0:1]
	v_mul_f32_e32 v175, v33, v32
	v_pk_mul_f32 v[70:71], v[34:35], v[66:67]
	v_cndmask_b32_e64 v33, v71, v67, s[28:29]
	v_cndmask_b32_e64 v32, v70, v66, s[30:31]
	v_pk_fma_f32 v[32:33], v[86:87], v[32:33], v[104:105]
	v_readlane_b32 s34, v176, 31
	v_mul_f32_e32 v32, v32, v33
	v_readlane_b32 s35, v176, 63
	v_add_u32_e32 v38, s33, v158
	v_mul_f32_dpp v32, v32, v32 row_shr:1 row_mask:0xf bank_mask:0xf
	v_rcp_f32_e32 v175, v175
	v_cndmask_b32_e64 v67, v67, v71, s[28:29]
	v_mul_f32_dpp v32, v32, v32 row_shr:2 row_mask:0xf bank_mask:0xf
	v_cndmask_b32_e64 v66, v66, v70, s[30:31]
	v_pk_mul_f32 v[66:67], v[86:87], v[66:67]
	v_mul_f32_dpp v32, v32, v32 row_shr:4 row_mask:0xf bank_mask:0xf
	s_nop 1
	v_mul_f32_dpp v32, v32, v32 row_shr:8 row_mask:0xf bank_mask:0xf
	v_mov_b32_e32 v34, 1.0
	s_nop 1
	v_mov_b32_dpp v34, v32 row_bcast:15 row_mask:0xa bank_mask:0xf
	v_mul_f32_e32 v180, v32, v34
	v_mov_b32_e32 v32, 1.0
	v_readlane_b32 s36, v180, 31
	v_readlane_b32 s37, v180, 63
	v_mov_b32_dpp v32, v180 wave_shr:1 row_mask:0xf bank_mask:0xf
	v_cndmask_b32_e64 v32, v32, 1.0, s[0:1]
	v_mul_f32_e32 v177, v33, v32
	v_mov_b32_e32 v32, s37
	v_mov_b32_e32 v33, s36
	v_cndmask_b32_e64 v63, v32, v33, s[2:3]
	v_mov_b32_e32 v32, s35
	v_mov_b32_e32 v33, s34
	v_cndmask_b32_e64 v62, v32, v33, s[2:3]
	v_add_u32_e32 v32, 0x400, v38
	v_add_u32_e32 v33, 1, v159
	v_cndmask_b32_e32 v32, v33, v32, vcc
	v_ashrrev_i32_e32 v33, 31, v32
	v_lshlrev_b64 v[32:33], 13, v[32:33]
	v_lshl_add_u64 v[34:35], v[116:117], 0, v[32:33]
	v_lshl_add_u64 v[36:37], v[118:119], 0, v[32:33]
	global_load_dwordx4 v[32:35], v[34:35], off offset:2048
	s_nop 0
	global_load_dwordx4 v[40:43], v[36:37], off
	v_add_u32_e32 v36, 0x401, v38
	v_cndmask_b32_e32 v36, v159, v36, vcc
	v_ashrrev_i32_e32 v37, 31, v36
	v_lshlrev_b64 v[36:37], 13, v[36:37]
	v_lshl_add_u64 v[38:39], v[116:117], 0, v[36:37]
	v_lshl_add_u64 v[44:45], v[118:119], 0, v[36:37]
	global_load_dwordx4 v[36:39], v[38:39], off offset:2048
	s_nop 0
	global_load_dwordx4 v[44:47], v[44:45], off
	v_cmp_le_f32_e64 s[34:35], 0, v68
	v_cmp_le_f32_e64 s[36:37], 0, v64
	v_cndmask_b32_e64 v179, v169, v57, s[34:35]
	v_cndmask_b32_e64 v178, v168, v56, s[36:37]
	v_cndmask_b32_e64 v57, v57, v169, s[34:35]
	v_cndmask_b32_e64 v56, v56, v168, s[36:37]
	v_pk_fma_f32 v[56:57], v[100:101], v[56:57], v[102:103]
	v_pk_mul_f32 v[168:169], v[100:101], v[178:179]
	v_mul_f32_e32 v57, v57, v56
	v_mov_b32_e32 v68, s42
	v_rcp_f32_e32 v177, v177
	v_mul_f32_dpp v57, v57, v57 row_shr:1 row_mask:0xf bank_mask:0xf
	s_nop 1
	v_mul_f32_dpp v57, v57, v57 row_shr:2 row_mask:0xf bank_mask:0xf
	s_nop 1
	v_mul_f32_dpp v57, v57, v57 row_shr:4 row_mask:0xf bank_mask:0xf
	s_nop 1
	v_mul_f32_dpp v57, v57, v57 row_shr:8 row_mask:0xf bank_mask:0xf
	v_mov_b32_e32 v64, 1.0
	s_nop 1
	v_mov_b32_dpp v64, v57 row_bcast:15 row_mask:0xa bank_mask:0xf
	v_mul_f32_e32 v64, v57, v64
	v_mov_b32_e32 v57, 1.0
	v_readlane_b32 s34, v64, 31
	v_readlane_b32 s35, v64, 63
	v_mov_b32_dpp v57, v64 wave_shr:1 row_mask:0xf bank_mask:0xf
	v_cndmask_b32_e64 v57, v57, 1.0, s[0:1]
	v_mul_f32_e32 v56, v56, v57
	v_rcp_f32_e32 v178, v56
	v_rcp_f32_e32 v179, v64
	v_mov_b32_e32 v56, s35
	v_mov_b32_e32 v64, s34
	v_cndmask_b32_e64 v56, v56, v64, s[2:3]
	v_rcp_f32_e32 v64, v74
	v_mov_b32_e32 v57, s50
	v_cndmask_b32_e64 v57, v57, v68, s[2:3]
	v_rcp_f32_e32 v68, v164
	v_pk_mul_f32 v[64:65], v[122:123], v[64:65]
	v_cndmask_b32_e64 v123, v127, v129, s[8:9]
	v_cndmask_b32_e64 v122, v126, v128, s[10:11]
	v_rcp_f32_e32 v164, v166
	v_pk_mul_f32 v[122:123], v[96:97], v[122:123]
	v_rcp_f32_e32 v166, v172
	v_pk_mul_f32 v[68:69], v[122:123], v[68:69]
	v_cndmask_b32_e64 v123, v131, v133, s[12:13]
	v_cndmask_b32_e64 v122, v130, v132, s[14:15]
	v_pk_mul_f32 v[122:123], v[94:95], v[122:123]
	v_rcp_f32_e32 v172, v174
	v_pk_mul_f32 v[124:125], v[122:123], v[164:165]
	v_cndmask_b32_e64 v123, v135, v137, s[16:17]
	v_cndmask_b32_e64 v122, v134, v136, s[18:19]
	v_pk_mul_f32 v[122:123], v[92:93], v[122:123]
	v_pk_mul_f32 v[168:169], v[168:169], v[178:179]
	v_pk_mul_f32 v[126:127], v[122:123], v[166:167]
	v_cndmask_b32_e64 v123, v139, v141, s[20:21]
	v_cndmask_b32_e64 v122, v138, v140, s[22:23]
	v_rcp_f32_e32 v174, v176
	v_pk_mul_f32 v[168:169], v[168:169], v[56:57] op_sel_hi:[1,0]
	v_pk_mul_f32 v[122:123], v[90:91], v[122:123]
	v_cvt_pk_bf16_f32 v71, v168, v169
	v_pk_mul_f32 v[128:129], v[122:123], v[172:173]
	v_cndmask_b32_e64 v123, v161, v163, s[24:25]
	v_cndmask_b32_e64 v122, v160, v162, s[26:27]
	v_mov_b32_e32 v70, v57
	v_pk_mul_f32 v[122:123], v[88:89], v[122:123]
	v_pk_mul_f32 v[64:65], v[64:65], v[70:71] op_sel:[1,0] op_sel_hi:[0,0]
	v_pk_mul_f32 v[130:131], v[122:123], v[174:175]
	v_cvt_pk_bf16_f32 v64, v64, v65
	v_add_u32_e32 v122, 0x8800, v150
	ds_write2_b32 v122, v71, v64 offset1:36
	v_pk_mul_f32 v[64:65], v[68:69], v[58:59] op_sel:[1,0] op_sel_hi:[0,0]
	v_cvt_pk_bf16_f32 v68, v64, v65
	v_mov_b32_e32 v64, v59
	v_pk_mul_f32 v[64:65], v[124:125], v[64:65] op_sel:[1,0] op_sel_hi:[0,0]
	v_cvt_pk_bf16_f32 v64, v64, v65
	ds_write2_b32 v122, v68, v64 offset0:72 offset1:108
	v_pk_mul_f32 v[64:65], v[126:127], v[60:61] op_sel:[1,0] op_sel_hi:[0,0]
	v_rcp_f32_e32 v176, v180
	v_cvt_pk_bf16_f32 v68, v64, v65
	v_mov_b32_e32 v64, v61
	v_pk_mul_f32 v[64:65], v[128:129], v[64:65] op_sel:[1,0] op_sel_hi:[0,0]
	v_cvt_pk_bf16_f32 v64, v64, v65
	ds_write2_b32 v122, v68, v64 offset0:144 offset1:180
	v_pk_mul_f32 v[64:65], v[130:131], v[62:63] op_sel:[1,0] op_sel_hi:[0,0]
	v_pk_mul_f32 v[66:67], v[66:67], v[176:177]
	v_cvt_pk_bf16_f32 v68, v64, v65
	v_mov_b32_e32 v64, v63
	v_pk_mul_f32 v[64:65], v[66:67], v[64:65] op_sel:[1,0] op_sel_hi:[0,0]
	v_cvt_pk_bf16_f32 v64, v64, v65
	ds_write2_b32 v122, v68, v64 offset0:216 offset1:252
	s_and_saveexec_b64 s[4:5], s[0:1]
	s_cbranch_execz .LBB0_286
	ds_write_b128 v145, v[56:59]
	ds_write_b128 v145, v[60:63] offset:16

.LBB0_288:
	s_waitcnt vmcnt(3)
	v_and_b32_e32 v51, 0xffff0000, v32
	s_waitcnt vmcnt(1)
	v_and_b32_e32 v50, 0xffff0000, v36
	v_mul_f32_e64 v48, |v51|, s45
	v_exp_f32_e32 v48, v48
	v_mul_f32_e64 v49, |v50|, s45
	v_exp_f32_e32 v49, v49
	v_cmp_le_f32_e32 vcc, 0, v50
	v_add_f32_e32 v52, 1.0, v48
	v_rcp_f32_e32 v56, v52
	v_add_f32_e32 v52, 1.0, v49
	v_rcp_f32_e32 v57, v52
	v_cmp_le_f32_e64 s[4:5], 0, v51
	v_lshlrev_b32_e32 v52, 16, v33
	v_pk_mul_f32 v[58:59], v[48:49], v[56:57]
	v_cmp_le_f32_e64 s[8:9], 0, v52
	v_cndmask_b32_e32 v49, v59, v57, vcc
	v_cndmask_b32_e64 v48, v58, v56, s[4:5]
	v_pk_fma_f32 v[48:49], v[98:99], v[48:49], v[120:121]
	v_and_b32_e32 v33, 0xffff0000, v33
	v_mul_f32_e32 v49, v48, v49
	v_cmp_le_f32_e64 s[12:13], 0, v33
	v_lshlrev_b32_e32 v55, 16, v34
	v_mul_f32_dpp v49, v49, v49 row_shr:1 row_mask:0xf bank_mask:0xf
	v_lshlrev_b32_e32 v54, 16, v38
	v_and_b32_e32 v34, 0xffff0000, v34
	v_mul_f32_dpp v49, v49, v49 row_shr:2 row_mask:0xf bank_mask:0xf
	v_and_b32_e32 v38, 0xffff0000, v38
	v_cmp_le_f32_e64 s[18:19], 0, v38
	v_mul_f32_dpp v49, v49, v49 row_shr:4 row_mask:0xf bank_mask:0xf
	v_cmp_le_f32_e64 s[20:21], 0, v34
	v_lshlrev_b32_e32 v130, 16, v35
	v_mul_f32_dpp v49, v49, v49 row_shr:8 row_mask:0xf bank_mask:0xf
	v_mov_b32_e32 v50, 1.0
	v_lshlrev_b32_e32 v129, 16, v39
	v_mov_b32_e32 v126, 1.0
	v_mov_b32_dpp v50, v49 row_bcast:15 row_mask:0xa bank_mask:0xf
	v_mul_f32_e32 v127, v49, v50
	v_lshlrev_b32_e32 v49, 16, v37
	v_mul_f32_e64 v50, |v52|, s45
	v_exp_f32_e32 v50, v50
	v_mul_f32_e64 v51, |v49|, s45
	v_exp_f32_e32 v51, v51
	v_cmp_le_f32_e64 s[6:7], 0, v49
	v_add_f32_e32 v53, 1.0, v50
	v_rcp_f32_e32 v60, v53
	v_add_f32_e32 v53, 1.0, v51
	v_rcp_f32_e32 v61, v53
	v_and_b32_e32 v37, 0xffff0000, v37
	v_cmp_le_f32_e64 s[10:11], 0, v37
	v_mul_f32_e64 v53, |v54|, s45
	v_pk_mul_f32 v[62:63], v[50:51], v[60:61]
	v_exp_f32_e32 v53, v53
	v_cndmask_b32_e64 v51, v63, v61, s[6:7]
	v_cndmask_b32_e64 v50, v62, v60, s[8:9]
	v_pk_fma_f32 v[114:115], v[96:97], v[50:51], v[114:115]
	v_mul_f32_e32 v49, v114, v115
	v_mov_b32_e32 v115, 1.0
	v_mov_b32_dpp v126, v127 wave_shr:1 row_mask:0xf bank_mask:0xf
	v_mul_f32_dpp v49, v49, v49 row_shr:1 row_mask:0xf bank_mask:0xf
	v_readlane_b32 s33, v127, 31
	v_readlane_b32 s36, v127, 63
	v_mul_f32_dpp v49, v49, v49 row_shr:2 row_mask:0xf bank_mask:0xf
	v_cndmask_b32_e32 v57, v57, v59, vcc
	v_cndmask_b32_e64 v56, v56, v58, s[4:5]
	v_mul_f32_dpp v49, v49, v49 row_shr:4 row_mask:0xf bank_mask:0xf
	v_pk_mul_f32 v[56:57], v[98:99], v[56:57]
	s_nop 0
	v_mul_f32_dpp v49, v49, v49 row_shr:8 row_mask:0xf bank_mask:0xf
	v_mov_b32_e32 v50, 1.0
	s_nop 1
	v_mov_b32_dpp v50, v49 row_bcast:15 row_mask:0xa bank_mask:0xf
	v_mul_f32_e32 v128, v49, v50
	v_mul_f32_e64 v49, |v33|, s45
	v_exp_f32_e32 v50, v49
	v_mul_f32_e64 v49, |v37|, s45
	v_exp_f32_e32 v51, v49
	v_add_f32_e32 v52, 1.0, v50
	v_rcp_f32_e32 v64, v52
	v_add_f32_e32 v52, 1.0, v51
	v_rcp_f32_e32 v65, v52
	v_mul_f32_e64 v52, |v55|, s45
	v_exp_f32_e32 v52, v52
	v_readlane_b32 s14, v128, 31
	v_pk_mul_f32 v[66:67], v[50:51], v[64:65]
	v_readlane_b32 s15, v128, 63
	v_cndmask_b32_e64 v51, v67, v65, s[10:11]
	v_cndmask_b32_e64 v50, v66, v64, s[12:13]
	v_pk_fma_f32 v[116:117], v[94:95], v[50:51], v[112:113]
	v_mov_b32_e32 v70, s14
	v_mul_f32_e32 v33, v116, v117
	v_mov_b32_e32 v49, 1.0
	s_nop 0
	v_mul_f32_dpp v33, v33, v33 row_shr:1 row_mask:0xf bank_mask:0xf
	v_mov_b32_dpp v49, v128 wave_shr:1 row_mask:0xf bank_mask:0xf
	v_cndmask_b32_e64 v49, v49, 1.0, s[0:1]
	v_mul_f32_dpp v33, v33, v33 row_shr:2 row_mask:0xf bank_mask:0xf
	v_mul_f32_e32 v49, v114, v49
	s_nop 0
	v_mul_f32_dpp v33, v33, v33 row_shr:4 row_mask:0xf bank_mask:0xf
	s_nop 1
	v_mul_f32_dpp v33, v33, v33 row_shr:8 row_mask:0xf bank_mask:0xf
	v_mov_b32_e32 v37, 1.0
	s_nop 1
	v_mov_b32_dpp v37, v33 row_bcast:15 row_mask:0xa bank_mask:0xf
	v_mul_f32_e32 v37, v33, v37
	v_mov_b32_e32 v33, 1.0
	v_readlane_b32 s16, v37, 31
	v_readlane_b32 s17, v37, 63
	v_mov_b32_dpp v33, v37 wave_shr:1 row_mask:0xf bank_mask:0xf
	v_mov_b32_e32 v51, s16
	v_mov_b32_e32 v50, s17
	v_cndmask_b32_e64 v51, v50, v51, s[2:3]
	v_add_f32_e32 v50, 1.0, v52
	v_rcp_f32_e32 v68, v50
	v_add_f32_e32 v50, 1.0, v53
	v_rcp_f32_e32 v69, v50
	v_mov_b32_e32 v50, s15
	v_cndmask_b32_e64 v50, v50, v70, s[2:3]
	v_cmp_le_f32_e64 s[14:15], 0, v54
	v_pk_mul_f32 v[70:71], v[52:53], v[68:69]
	v_cmp_le_f32_e64 s[16:17], 0, v55
	v_cndmask_b32_e64 v53, v71, v69, s[14:15]
	v_cndmask_b32_e64 v33, v33, 1.0, s[0:1]
	v_cndmask_b32_e64 v52, v70, v68, s[16:17]
	v_pk_fma_f32 v[118:119], v[92:93], v[52:53], v[110:111]
	v_mul_f32_e32 v52, v118, v119
	v_mul_f32_e32 v33, v116, v33
	s_nop 0
	v_mul_f32_dpp v52, v52, v52 row_shr:1 row_mask:0xf bank_mask:0xf
	s_nop 1
	v_mul_f32_dpp v52, v52, v52 row_shr:2 row_mask:0xf bank_mask:0xf
	s_nop 1
	v_mul_f32_dpp v52, v52, v52 row_shr:4 row_mask:0xf bank_mask:0xf
	s_nop 1
	v_mul_f32_dpp v52, v52, v52 row_shr:8 row_mask:0xf bank_mask:0xf
	v_mov_b32_e32 v53, 1.0
	s_nop 1
	v_mov_b32_dpp v53, v52 row_bcast:15 row_mask:0xa bank_mask:0xf
	v_mul_f32_e32 v117, v52, v53
	v_mul_f32_e64 v52, |v34|, s45
	v_exp_f32_e32 v52, v52
	v_mul_f32_e64 v53, |v38|, s45
	v_exp_f32_e32 v53, v53
	v_add_f32_e32 v54, 1.0, v52
	v_rcp_f32_e32 v110, v54
	v_add_f32_e32 v54, 1.0, v53
	v_rcp_f32_e32 v111, v54
	v_readlane_b32 s22, v117, 31
	v_readlane_b32 s23, v117, 63
	v_mov_b32_dpp v115, v117 wave_shr:1 row_mask:0xf bank_mask:0xf
	v_pk_mul_f32 v[112:113], v[52:53], v[110:111]
	s_nop 0
	v_cndmask_b32_e64 v53, v113, v111, s[18:19]
	v_cndmask_b32_e64 v52, v112, v110, s[20:21]
	v_pk_fma_f32 v[108:109], v[90:91], v[52:53], v[108:109]
	v_mul_f32_e64 v52, |v130|, s45
	v_mul_f32_e32 v34, v108, v109
	v_exp_f32_e32 v54, v52
	v_mul_f32_e64 v52, |v129|, s45
	v_mul_f32_dpp v34, v34, v34 row_shr:1 row_mask:0xf bank_mask:0xf
	v_exp_f32_e32 v55, v52
	v_mov_b32_e32 v109, 1.0
	v_mul_f32_dpp v34, v34, v34 row_shr:2 row_mask:0xf bank_mask:0xf
	s_nop 1
	v_mul_f32_dpp v34, v34, v34 row_shr:4 row_mask:0xf bank_mask:0xf
	s_nop 1
	v_mul_f32_dpp v34, v34, v34 row_shr:8 row_mask:0xf bank_mask:0xf
	v_mov_b32_e32 v38, 1.0
	s_nop 1
	v_mov_b32_dpp v38, v34 row_bcast:15 row_mask:0xa bank_mask:0xf
	v_mul_f32_e32 v119, v34, v38
	s_nop 0
	v_readlane_b32 s24, v119, 31
	v_readlane_b32 s25, v119, 63
	v_mov_b32_dpp v109, v119 wave_shr:1 row_mask:0xf bank_mask:0xf
	v_mov_b32_e32 v38, s24
	v_mov_b32_e32 v34, s25
	v_cndmask_b32_e64 v53, v34, v38, s[2:3]
	v_add_f32_e32 v34, 1.0, v54
	v_rcp_f32_e32 v120, v34
	v_add_f32_e32 v34, 1.0, v55
	v_rcp_f32_e32 v121, v34
	v_mov_b32_e32 v34, s23
	v_mov_b32_e32 v38, s22
	v_cmp_le_f32_e64 s[22:23], 0, v129
	v_pk_mul_f32 v[124:125], v[54:55], v[120:121]
	v_cmp_le_f32_e64 s[24:25], 0, v130
	v_cndmask_b32_e64 v55, v125, v121, s[22:23]
	v_cndmask_b32_e64 v52, v34, v38, s[2:3]
	v_cndmask_b32_e64 v54, v124, v120, s[24:25]
	v_pk_fma_f32 v[106:107], v[88:89], v[54:55], v[106:107]
	v_mul_f32_e32 v34, v106, v107
	v_and_b32_e32 v54, 0xffff0000, v39
	v_and_b32_e32 v107, 0xffff0000, v35
	v_mul_f32_dpp v34, v34, v34 row_shr:1 row_mask:0xf bank_mask:0xf
	v_mul_f32_e64 v35, |v54|, s45
	v_exp_f32_e32 v35, v35
	v_mul_f32_dpp v34, v34, v34 row_shr:2 row_mask:0xf bank_mask:0xf
	v_add_f32_e32 v39, 1.0, v35
	v_rcp_f32_e32 v39, v39
	v_mul_f32_dpp v34, v34, v34 row_shr:4 row_mask:0xf bank_mask:0xf
	v_cmp_le_f32_e64 s[26:27], 0, v54
	v_cmp_le_f32_e64 s[28:29], 0, v107
	v_mul_f32_dpp v34, v34, v34 row_shr:8 row_mask:0xf bank_mask:0xf
	v_mov_b32_e32 v38, 1.0
	v_mov_b32_e32 v130, 1.0
	s_nop 0
	v_mov_b32_dpp v38, v34 row_bcast:15 row_mask:0xa bank_mask:0xf
	v_mul_f32_e32 v129, v34, v38
	v_mul_f32_e64 v34, |v107|, s45
	v_exp_f32_e32 v34, v34
	v_mov_b32_dpp v130, v129 wave_shr:1 row_mask:0xf bank_mask:0xf
	v_readlane_b32 s30, v129, 31
	v_readlane_b32 s31, v129, 63
	v_add_f32_e32 v38, 1.0, v34
	v_rcp_f32_e32 v38, v38
	v_mov_b32_e32 v107, s30
	v_pk_mul_f32 v[34:35], v[34:35], v[38:39]
	s_nop 0
	v_cndmask_b32_e64 v55, v35, v39, s[26:27]
	v_cndmask_b32_e64 v54, v34, v38, s[28:29]
	v_pk_fma_f32 v[104:105], v[86:87], v[54:55], v[104:105]
	v_mul_f32_e32 v54, v104, v105
	v_mov_b32_e32 v105, 1.0
	v_cndmask_b32_e64 v35, v39, v35, s[26:27]
	v_mul_f32_dpp v54, v54, v54 row_shr:1 row_mask:0xf bank_mask:0xf
	v_cndmask_b32_e64 v34, v38, v34, s[28:29]
	v_pk_mul_f32 v[34:35], v[86:87], v[34:35]
	v_mul_f32_dpp v54, v54, v54 row_shr:2 row_mask:0xf bank_mask:0xf
	s_nop 1
	v_mul_f32_dpp v54, v54, v54 row_shr:4 row_mask:0xf bank_mask:0xf
	s_nop 1
	v_mul_f32_dpp v54, v54, v54 row_shr:8 row_mask:0xf bank_mask:0xf
	v_mov_b32_e32 v55, 1.0
	s_nop 1
	v_mov_b32_dpp v55, v54 row_bcast:15 row_mask:0xa bank_mask:0xf
	v_mul_f32_e32 v131, v54, v55
	s_nop 0
	v_readlane_b32 s34, v131, 31
	v_mov_b32_dpp v105, v131 wave_shr:1 row_mask:0xf bank_mask:0xf
	v_readlane_b32 s35, v131, 63
	v_mov_b32_e32 v55, s34
	v_cndmask_b32_e64 v105, v105, 1.0, s[0:1]
	v_mov_b32_e32 v54, s35
	v_cndmask_b32_e64 v55, v54, v55, s[2:3]
	v_mov_b32_e32 v54, s31
	v_mul_f32_e32 v105, v104, v105
	v_cndmask_b32_e64 v104, v130, 1.0, s[0:1]
	v_cndmask_b32_e64 v54, v54, v107, s[2:3]
	v_mul_f32_e32 v107, v106, v104
	v_cndmask_b32_e64 v104, v109, 1.0, s[0:1]
	v_mul_f32_e32 v109, v108, v104
	v_cndmask_b32_e64 v104, v115, 1.0, s[0:1]
	v_mul_f32_e32 v115, v118, v104
	v_cndmask_b32_e64 v104, v126, 1.0, s[0:1]
	v_mul_f32_e32 v48, v48, v104
	v_lshlrev_b32_e32 v130, 16, v32
	v_rcp_f32_e32 v104, v48
	v_lshlrev_b32_e32 v48, 16, v36
	v_mul_f32_e64 v32, |v130|, s45
	v_rcp_f32_e32 v108, v33
	v_exp_f32_e32 v32, v32
	v_mul_f32_e64 v33, |v48|, s45
	v_exp_f32_e32 v33, v33
	v_rcp_f32_e32 v106, v49
	v_add_f32_e32 v49, 1.0, v32
	v_rcp_f32_e32 v114, v49
	v_add_f32_e32 v49, 1.0, v33
	v_rcp_f32_e32 v36, v115
	v_rcp_f32_e32 v115, v49
	v_cmp_le_f32_e64 s[30:31], 0, v48
	v_cmp_le_f32_e64 s[34:35], 0, v130
	v_rcp_f32_e32 v126, v105
	v_pk_mul_f32 v[32:33], v[32:33], v[114:115]
	v_mov_b32_e32 v105, 1.0
	v_cndmask_b32_e64 v49, v33, v115, s[30:31]
	v_cndmask_b32_e64 v48, v32, v114, s[34:35]
	v_pk_fma_f32 v[102:103], v[100:101], v[48:49], v[102:103]
	v_mul_f32_e32 v48, v102, v103
	v_rcp_f32_e32 v116, v109
	v_rcp_f32_e32 v109, v37
	v_mul_f32_dpp v48, v48, v48 row_shr:1 row_mask:0xf bank_mask:0xf
	v_rcp_f32_e32 v37, v117
	v_rcp_f32_e32 v118, v107
	v_mul_f32_dpp v48, v48, v48 row_shr:2 row_mask:0xf bank_mask:0xf
	v_rcp_f32_e32 v117, v119
	v_cndmask_b32_e64 v33, v115, v33, s[30:31]
	v_mul_f32_dpp v48, v48, v48 row_shr:4 row_mask:0xf bank_mask:0xf
	v_cndmask_b32_e64 v32, v114, v32, s[34:35]
	v_pk_mul_f32 v[32:33], v[100:101], v[32:33]
	v_mul_f32_dpp v48, v48, v48 row_shr:8 row_mask:0xf bank_mask:0xf
	v_mov_b32_e32 v49, 1.0
	v_rcp_f32_e32 v119, v129
	v_mov_b32_e32 v38, v55
	v_mov_b32_dpp v49, v48 row_bcast:15 row_mask:0xa bank_mask:0xf
	v_mul_f32_e32 v103, v48, v49
	v_mov_b32_e32 v48, s36
	v_mov_b32_e32 v49, s33
	v_mov_b32_dpp v105, v103 wave_shr:1 row_mask:0xf bank_mask:0xf
	v_cndmask_b32_e64 v105, v105, 1.0, s[0:1]
	v_mul_f32_e32 v102, v102, v105
	v_rcp_f32_e32 v105, v127
	v_cndmask_b32_e64 v49, v48, v49, s[2:3]
	v_mov_b32_e32 v58, v49
	v_readlane_b32 s37, v103, 31
	v_pk_mul_f32 v[56:57], v[56:57], v[104:105]
	v_readlane_b32 s42, v103, 63
	v_pk_mul_f32 v[56:57], v[56:57], v[58:59] op_sel_hi:[1,0]
	v_cndmask_b32_e64 v59, v61, v63, s[6:7]
	v_cndmask_b32_e64 v58, v60, v62, s[8:9]
	v_cndmask_b32_e64 v61, v65, v67, s[10:11]
	v_cndmask_b32_e64 v60, v64, v66, s[12:13]
	v_pk_mul_f32 v[60:61], v[94:95], v[60:61]
	v_mov_b32_e32 v62, v51
	v_pk_mul_f32 v[60:61], v[60:61], v[108:109]
	v_mov_b32_e32 v48, s42
	v_mov_b32_e32 v107, s37
	v_rcp_f32_e32 v102, v102
	v_rcp_f32_e32 v103, v103
	v_pk_mul_f32 v[60:61], v[60:61], v[62:63] op_sel_hi:[1,0]
	v_cndmask_b32_e64 v63, v69, v71, s[14:15]
	v_cndmask_b32_e64 v62, v68, v70, s[16:17]
	v_cndmask_b32_e64 v48, v48, v107, s[2:3]
	v_rcp_f32_e32 v107, v128
	v_pk_mul_f32 v[62:63], v[92:93], v[62:63]
	v_rcp_f32_e32 v127, v131
	v_pk_mul_f32 v[36:37], v[62:63], v[36:37]
	v_cndmask_b32_e64 v63, v111, v113, s[18:19]
	v_cndmask_b32_e64 v62, v110, v112, s[20:21]
	v_pk_mul_f32 v[62:63], v[90:91], v[62:63]
	v_pk_mul_f32 v[32:33], v[32:33], v[102:103]
	v_pk_mul_f32 v[58:59], v[96:97], v[58:59]
	v_pk_mul_f32 v[62:63], v[62:63], v[116:117]
	v_mov_b32_e32 v64, v53
	v_pk_mul_f32 v[32:33], v[32:33], v[48:49] op_sel_hi:[1,0]
	v_pk_mul_f32 v[58:59], v[58:59], v[106:107]
	v_pk_mul_f32 v[62:63], v[62:63], v[64:65] op_sel_hi:[1,0]
	v_cndmask_b32_e64 v65, v121, v125, s[22:23]
	v_cndmask_b32_e64 v64, v120, v124, s[24:25]
	v_pk_mul_f32 v[58:59], v[58:59], v[50:51] op_sel_hi:[1,0]
	v_pk_mul_f32 v[64:65], v[88:89], v[64:65]
	v_cvt_pk_bf16_f32 v32, v32, v33
	v_cvt_pk_bf16_f32 v33, v56, v57
	v_pk_mul_f32 v[36:37], v[36:37], v[52:53] op_sel_hi:[1,0]
	v_pk_mul_f32 v[64:65], v[64:65], v[118:119]
	v_pk_mul_f32 v[34:35], v[34:35], v[126:127]
	ds_write2_b32 v122, v32, v33 offset1:36
	v_cvt_pk_bf16_f32 v32, v58, v59
	v_cvt_pk_bf16_f32 v33, v60, v61
	v_pk_mul_f32 v[64:65], v[64:65], v[54:55] op_sel_hi:[1,0]
	v_pk_mul_f32 v[34:35], v[34:35], v[38:39] op_sel_hi:[1,0]
	ds_write2_b32 v122, v32, v33 offset0:72 offset1:108
	v_cvt_pk_bf16_f32 v32, v36, v37
	v_cvt_pk_bf16_f32 v33, v62, v63
	ds_write2_b32 v122, v32, v33 offset0:144 offset1:180
	v_cvt_pk_bf16_f32 v32, v64, v65
	v_cvt_pk_bf16_f32 v33, v34, v35
	ds_write2_b32 v122, v32, v33 offset0:216 offset1:252
	s_and_saveexec_b64 s[4:5], s[0:1]
	s_cbranch_execz .LBB0_290
	ds_write_b128 v145, v[48:51]
	ds_write_b128 v145, v[52:55] offset:16

.LBB0_388:
	s_waitcnt vmcnt(0)
	v_lshlrev_b32_e32 v81, 16, v34
	v_and_b32_e32 v106, 0xffff0000, v34
	v_mul_f32_e64 v74, |v81|, s60
	v_lshlrev_b32_e32 v107, 16, v38
	v_and_b32_e32 v114, 0xffff0000, v38
	v_exp_f32_e32 v76, v74
	v_mul_f32_e64 v74, |v106|, s60
	v_mul_f32_e64 v104, |v107|, s60
	v_mul_f32_e64 v105, |v114|, s60
	v_exp_f32_e32 v77, v74
	v_exp_f32_e32 v104, v104
	v_exp_f32_e32 v105, v105
	v_add_f32_e32 v74, 1.0, v76
	v_add_f32_e32 v75, 1.0, v77
	v_add_f32_e32 v108, 1.0, v104
	v_add_f32_e32 v109, 1.0, v105
	v_rcp_f32_e32 v74, v74
	v_rcp_f32_e32 v75, v75
	v_rcp_f32_e32 v108, v108
	v_rcp_f32_e32 v109, v109
	v_cmp_le_f32_e32 vcc, 0, v106
	v_pk_mul_f32 v[110:111], v[76:77], v[74:75]
	v_cmp_le_f32_e64 s[22:23], 0, v81
	v_pk_mul_f32 v[112:113], v[104:105], v[108:109]
	v_cmp_le_f32_e64 s[24:25], 0, v114
	v_cmp_le_f32_e64 s[26:27], 0, v107
	v_cndmask_b32_e32 v77, v111, v75, vcc
	v_cndmask_b32_e64 v76, v110, v74, s[22:23]
	v_cndmask_b32_e64 v105, v113, v109, s[24:25]
	v_cndmask_b32_e64 v104, v112, v108, s[26:27]
	v_pk_fma_f32 v[76:77], v[94:95], v[76:77], v[82:83]
	v_pk_fma_f32 v[104:105], v[94:95], v[104:105], v[82:83]
	v_pk_mul_f32 v[104:105], v[76:77], v[104:105]
	v_lshlrev_b32_e32 v118, 16, v35
	s_nop 0
	v_mul_f32_dpp v104, v104, v104 row_shr:1 row_mask:0xf bank_mask:0xf
	v_mul_f32_dpp v105, v105, v105 row_shr:1 row_mask:0xf bank_mask:0xf
	v_and_b32_e32 v119, 0xffff0000, v35
	v_mul_f32_dpp v104, v104, v104 row_shr:2 row_mask:0xf bank_mask:0xf
	v_mul_f32_dpp v105, v105, v105 row_shr:2 row_mask:0xf bank_mask:0xf
	v_lshlrev_b32_e32 v126, 16, v39
	v_mul_f32_dpp v104, v104, v104 row_shr:4 row_mask:0xf bank_mask:0xf
	v_mul_f32_dpp v105, v105, v105 row_shr:4 row_mask:0xf bank_mask:0xf
	v_and_b32_e32 v127, 0xffff0000, v39
	v_mul_f32_dpp v104, v104, v104 row_shr:8 row_mask:0xf bank_mask:0xf
	v_mul_f32_dpp v105, v105, v105 row_shr:8 row_mask:0xf bank_mask:0xf
	v_mul_f32_e64 v116, |v126|, s60
	v_mul_f32_dpp v104, v104, v104 row_bcast:15 row_mask:0xa bank_mask:0xf
	v_mul_f32_dpp v105, v105, v105 row_bcast:15 row_mask:0xa bank_mask:0xf
	v_mul_f32_e64 v106, |v118|, s60
	v_mul_f32_e64 v107, |v119|, s60
	v_exp_f32_e32 v106, v106
	v_exp_f32_e32 v107, v107
	v_mul_f32_e64 v117, |v127|, s60
	v_exp_f32_e32 v116, v116
	v_exp_f32_e32 v117, v117
	v_add_f32_e32 v114, 1.0, v106
	v_add_f32_e32 v115, 1.0, v107
	v_rcp_f32_e32 v114, v114
	v_rcp_f32_e32 v115, v115
	v_add_f32_e32 v120, 1.0, v116
	v_add_f32_e32 v121, 1.0, v117
	v_rcp_f32_e32 v120, v120
	v_rcp_f32_e32 v121, v121
	v_pk_mul_f32 v[122:123], v[106:107], v[114:115]
	v_cmp_le_f32_e64 s[28:29], 0, v119
	v_cmp_le_f32_e64 s[30:31], 0, v118
	v_pk_mul_f32 v[124:125], v[116:117], v[120:121]
	v_cndmask_b32_e64 v107, v123, v115, s[28:29]
	v_cndmask_b32_e64 v106, v122, v114, s[30:31]
	v_cmp_le_f32_e64 s[34:35], 0, v127
	v_cmp_le_f32_e64 s[36:37], 0, v126
	v_pk_fma_f32 v[118:119], v[96:97], v[106:107], v[84:85]
	v_cndmask_b32_e64 v107, v125, v121, s[34:35]
	v_cndmask_b32_e64 v106, v124, v120, s[36:37]
	v_pk_fma_f32 v[106:107], v[96:97], v[106:107], v[84:85]
	v_pk_mul_f32 v[106:107], v[118:119], v[106:107]
	v_lshlrev_b32_e32 v130, 16, v36
	s_nop 0
	v_mul_f32_dpp v106, v106, v106 row_shr:1 row_mask:0xf bank_mask:0xf
	v_mul_f32_dpp v107, v107, v107 row_shr:1 row_mask:0xf bank_mask:0xf
	v_and_b32_e32 v131, 0xffff0000, v36
	v_mul_f32_dpp v106, v106, v106 row_shr:2 row_mask:0xf bank_mask:0xf
	v_mul_f32_dpp v107, v107, v107 row_shr:2 row_mask:0xf bank_mask:0xf
	v_lshlrev_b32_e32 v138, 16, v40
	v_mul_f32_dpp v106, v106, v106 row_shr:4 row_mask:0xf bank_mask:0xf
	v_mul_f32_dpp v107, v107, v107 row_shr:4 row_mask:0xf bank_mask:0xf
	v_and_b32_e32 v139, 0xffff0000, v40
	v_mul_f32_dpp v106, v106, v106 row_shr:8 row_mask:0xf bank_mask:0xf
	v_mul_f32_dpp v107, v107, v107 row_shr:8 row_mask:0xf bank_mask:0xf
	v_mul_f32_e64 v128, |v138|, s60
	v_mul_f32_dpp v106, v106, v106 row_bcast:15 row_mask:0xa bank_mask:0xf
	v_mul_f32_dpp v107, v107, v107 row_bcast:15 row_mask:0xa bank_mask:0xf
	v_mul_f32_e64 v116, |v130|, s60
	v_mul_f32_e64 v117, |v131|, s60
	v_exp_f32_e32 v116, v116
	v_exp_f32_e32 v117, v117
	v_mul_f32_e64 v129, |v139|, s60
	v_exp_f32_e32 v128, v128
	v_exp_f32_e32 v129, v129
	v_add_f32_e32 v126, 1.0, v116
	v_add_f32_e32 v127, 1.0, v117
	v_rcp_f32_e32 v126, v126
	v_rcp_f32_e32 v127, v127
	v_add_f32_e32 v132, 1.0, v128
	v_add_f32_e32 v133, 1.0, v129
	v_rcp_f32_e32 v132, v132
	v_rcp_f32_e32 v133, v133
	v_pk_mul_f32 v[134:135], v[116:117], v[126:127]
	v_cmp_le_f32_e64 s[38:39], 0, v131
	v_cmp_le_f32_e64 s[40:41], 0, v130
	v_pk_mul_f32 v[136:137], v[128:129], v[132:133]
	v_cndmask_b32_e64 v117, v135, v127, s[38:39]
	v_cndmask_b32_e64 v116, v134, v126, s[40:41]
	v_cmp_le_f32_e64 s[42:43], 0, v139
	v_cmp_le_f32_e64 s[44:45], 0, v138
	v_pk_fma_f32 v[128:129], v[98:99], v[116:117], v[86:87]
	v_cndmask_b32_e64 v117, v137, v133, s[42:43]
	v_cndmask_b32_e64 v116, v136, v132, s[44:45]
	v_pk_fma_f32 v[116:117], v[98:99], v[116:117], v[86:87]
	v_pk_mul_f32 v[116:117], v[128:129], v[116:117]
	v_lshlrev_b32_e32 v187, 16, v37
	s_nop 0
	v_mul_f32_dpp v116, v116, v116 row_shr:1 row_mask:0xf bank_mask:0xf
	v_mul_f32_dpp v117, v117, v117 row_shr:1 row_mask:0xf bank_mask:0xf
	v_and_b32_e32 v188, 0xffff0000, v37
	v_mul_f32_dpp v116, v116, v116 row_shr:2 row_mask:0xf bank_mask:0xf
	v_mul_f32_dpp v117, v117, v117 row_shr:2 row_mask:0xf bank_mask:0xf
	v_lshlrev_b32_e32 v189, 16, v41
	v_mul_f32_dpp v116, v116, v116 row_shr:4 row_mask:0xf bank_mask:0xf
	v_mul_f32_dpp v117, v117, v117 row_shr:4 row_mask:0xf bank_mask:0xf
	v_and_b32_e32 v190, 0xffff0000, v41
	v_mul_f32_dpp v116, v116, v116 row_shr:8 row_mask:0xf bank_mask:0xf
	v_mul_f32_dpp v117, v117, v117 row_shr:8 row_mask:0xf bank_mask:0xf
	v_mul_f32_e64 v140, |v189|, s60
	v_mul_f32_dpp v116, v116, v116 row_bcast:15 row_mask:0xa bank_mask:0xf
	v_mul_f32_dpp v117, v117, v117 row_bcast:15 row_mask:0xa bank_mask:0xf
	v_mul_f32_e64 v130, |v187|, s60
	v_mul_f32_e64 v131, |v188|, s60
	v_exp_f32_e32 v130, v130
	v_exp_f32_e32 v131, v131
	v_mul_f32_e64 v141, |v190|, s60
	v_exp_f32_e32 v140, v140
	v_exp_f32_e32 v141, v141
	v_add_f32_e32 v138, 1.0, v130
	v_add_f32_e32 v139, 1.0, v131
	v_rcp_f32_e32 v138, v138
	v_rcp_f32_e32 v139, v139
	v_add_f32_e32 v142, 1.0, v140
	v_add_f32_e32 v143, 1.0, v141
	v_rcp_f32_e32 v142, v142
	v_rcp_f32_e32 v143, v143
	v_pk_mul_f32 v[144:145], v[130:131], v[138:139]
	v_cmp_le_f32_e64 s[46:47], 0, v188
	v_cmp_le_f32_e64 s[48:49], 0, v187
	v_pk_mul_f32 v[146:147], v[140:141], v[142:143]
	v_cndmask_b32_e64 v131, v145, v139, s[46:47]
	v_cndmask_b32_e64 v130, v144, v138, s[48:49]
	v_cmp_le_f32_e64 s[50:51], 0, v190
	v_cmp_le_f32_e64 s[52:53], 0, v189
	v_pk_fma_f32 v[140:141], v[100:101], v[130:131], v[88:89]
	v_cndmask_b32_e64 v131, v147, v143, s[50:51]
	v_cndmask_b32_e64 v130, v146, v142, s[52:53]
	v_pk_fma_f32 v[130:131], v[100:101], v[130:131], v[88:89]
	v_pk_mul_f32 v[130:131], v[140:141], v[130:131]
	v_mov_b32_e32 v81, 1.0
	s_nop 0
	v_mul_f32_dpp v130, v130, v130 row_shr:1 row_mask:0xf bank_mask:0xf
	v_mul_f32_dpp v131, v131, v131 row_shr:1 row_mask:0xf bank_mask:0xf
	v_mov_b32_e32 v182, 1.0
	v_mul_f32_dpp v130, v130, v130 row_shr:2 row_mask:0xf bank_mask:0xf
	v_mul_f32_dpp v131, v131, v131 row_shr:2 row_mask:0xf bank_mask:0xf
	v_mov_b32_e32 v183, 1.0
	v_mul_f32_dpp v130, v130, v130 row_shr:4 row_mask:0xf bank_mask:0xf
	v_mul_f32_dpp v131, v131, v131 row_shr:4 row_mask:0xf bank_mask:0xf
	v_mov_b32_e32 v184, 1.0
	v_mul_f32_dpp v130, v130, v130 row_shr:8 row_mask:0xf bank_mask:0xf
	v_mul_f32_dpp v131, v131, v131 row_shr:8 row_mask:0xf bank_mask:0xf
	v_mov_b32_e32 v188, 1.0
	v_mov_b32_e32 v189, 1.0
	v_mov_b32_e32 v185, 1.0
	v_mov_b32_dpp v188, v130 row_bcast:15 row_mask:0xa bank_mask:0xf
	v_mov_b32_dpp v189, v131 row_bcast:15 row_mask:0xa bank_mask:0xf
	v_mov_b32_e32 v186, 1.0
	v_pk_mul_f32 v[130:131], v[130:131], v[188:189]
	v_mov_b32_e32 v187, 1.0
	v_mov_b32_e32 v188, 1.0
	v_mov_b32_dpp v81, v104 wave_shr:1 row_mask:0xf bank_mask:0xf
	v_readlane_b32 s56, v104, 31
	v_readlane_b32 s57, v104, 63
	v_mov_b32_dpp v182, v105 wave_shr:1 row_mask:0xf bank_mask:0xf
	v_readlane_b32 s62, v105, 31
	v_readlane_b32 s63, v105, 63
	v_mov_b32_dpp v183, v106 wave_shr:1 row_mask:0xf bank_mask:0xf
	v_readlane_b32 s64, v106, 31
	v_readlane_b32 s65, v106, 63
	v_mov_b32_dpp v184, v107 wave_shr:1 row_mask:0xf bank_mask:0xf
	v_readlane_b32 s66, v107, 31
	v_readlane_b32 s67, v107, 63
	v_mov_b32_dpp v185, v116 wave_shr:1 row_mask:0xf bank_mask:0xf
	v_readlane_b32 s74, v116, 31
	v_readlane_b32 s96, v116, 63
	v_mov_b32_dpp v186, v117 wave_shr:1 row_mask:0xf bank_mask:0xf
	v_readlane_b32 s97, v117, 31
	v_readlane_b32 s84, v117, 63
	v_mov_b32_dpp v187, v130 wave_shr:1 row_mask:0xf bank_mask:0xf
	v_readlane_b32 s85, v130, 31
	v_readlane_b32 s87, v130, 63
	v_mov_b32_dpp v188, v131 wave_shr:1 row_mask:0xf bank_mask:0xf
	v_readlane_b32 s86, v131, 31
	s_cmpk_eq_i32 s55, 0x3c0
	v_readlane_b32 s68, v131, 63
	s_cbranch_scc1 .LBB0_390
	v_add_u32_e32 v40, s55, v179
	v_add_u32_e32 v34, 64, v40
	v_add_u32_e32 v35, 1, v180
	v_add_u32_e32 v40, 0x41, v40
	v_cndmask_b32_e64 v34, v35, v34, s[20:21]
	v_cndmask_b32_e64 v40, v180, v40, s[20:21]
	v_ashrrev_i32_e32 v35, 31, v34
	v_ashrrev_i32_e32 v41, 31, v40
	v_lshlrev_b64 v[38:39], 13, v[34:35]
	v_lshlrev_b64 v[40:41], 13, v[40:41]
	v_lshl_add_u64 v[34:35], s[88:89], 0, v[38:39]
	v_lshl_add_u64 v[54:55], s[88:89], 0, v[40:41]
	v_lshl_add_u64 v[36:37], v[34:35], 0, v[0:1]
	v_lshl_add_u64 v[34:35], v[34:35], 0, v[92:93]
	v_lshl_add_u64 v[38:39], v[90:91], 0, v[38:39]
	v_lshl_add_u64 v[50:51], v[54:55], 0, v[0:1]
	global_load_dwordx4 v[42:45], v[36:37], off
	s_nop 0
	global_load_dwordx4 v[34:37], v[34:35], off offset:2048
	s_nop 0
	global_load_dwordx4 v[46:49], v[38:39], off
	s_nop 0
	global_load_dwordx4 v[50:53], v[50:51], off
	v_lshl_add_u64 v[38:39], v[54:55], 0, v[92:93]
	v_lshl_add_u64 v[54:55], v[90:91], 0, v[40:41]
	global_load_dwordx4 v[38:41], v[38:39], off offset:2048
	s_nop 0
	global_load_dwordx4 v[54:57], v[54:55], off

.LBB0_807:
	s_or_b64 exec, exec, s[14:15]
	s_cmp_gt_u32 s30, 63
	s_cbranch_scc1 .LBB0_825
	s_memrealtime s[14:15]
	buffer_inv sc1
	s_lshl_b32 s16, s10, 6
	s_ashr_i32 s17, s16, 31
	s_lshl_b64 s[16:17], s[16:17], 2
	s_add_u32 s16, s11, s16
	s_addc_u32 s17, s18, s17
	v_mov_b32_e32 v135, 0
	s_waitcnt lgkmcnt(0)
	v_mov_b64_e32 v[132:133], 0x1e8481
	s_branch .LBB0_811

.LBB0_821:
	s_and_saveexec_b64 s[14:15], s[4:5]
	s_cbranch_execz .LBB0_824
	s_waitcnt vmcnt(0)
	s_and_b64 exec, exec, s[2:3]
	v_cndmask_b32_e64 v132, 0, 1, s[10:11]
	v_mov_b32_e32 v133, 0
	ds_write_b32 v133, v132 offset:10240

.LBB0_1070:
	s_or_b64 exec, exec, s[10:11]
	s_cmp_gt_u32 s25, 63
	s_cbranch_scc1 .LBB0_1088
	s_memrealtime s[10:11]
	buffer_inv sc1
	s_lshl_b32 s14, s24, 6
	s_ashr_i32 s15, s14, 31
	s_lshl_b64 s[14:15], s[14:15], 2
	s_add_u32 s14, s16, s14
	s_addc_u32 s15, s17, s15
	v_mov_b32_e32 v133, 0
	v_mov_b64_e32 v[130:131], 0x1e8481
	s_branch .LBB0_1074

.LBB0_1084:
	s_and_saveexec_b64 s[14:15], s[4:5]
	s_cbranch_execz .LBB0_1087
	s_waitcnt vmcnt(0)
	s_and_b64 exec, exec, s[2:3]
	v_cndmask_b32_e64 v130, 0, 1, s[10:11]
	v_mov_b32_e32 v131, 0
	ds_write_b32 v131, v130 offset:10240
